# q-projection epilogue reads the rope table from an LDS copy (no vmcnt(0) between its 12 output blocks)
# speedup vs baseline: 1.0231x; 1.0025x over previous
; DEV float bflo(unsigned w) { return __uint_as_float(w << 16); }
; DEV float bfhi(unsigned w) { return __uint_as_float(w & 0xffff0000u); }
; DEV void row_scales(const u16* __restrict__ zrow0, int col0, int ncol, float* rs, int tid) {
;   if (tid >= 384) return;
;   const int r = tid >> 1, h = tid & 1, lane = tid & 63;
;   const u16* s = zrow0 + (long)r * NINP + col0 + h * (ncol / 2);
;   float ss = 0.f;
;   for (int i = 0; i < ncol / 2; i += 8) {
;     uint4 v = *(const uint4*)(s + i);
;     ss += bflo(v.x) * bflo(v.x) + bfhi(v.x) * bfhi(v.x) + bflo(v.y) * bflo(v.y) + bfhi(v.y) * bfhi(v.y) +
;           bflo(v.z) * bflo(v.z) + bfhi(v.z) * bfhi(v.z) + bflo(v.w) * bflo(v.w) + bfhi(v.w) * bfhi(v.w);
;   }
;   ss += shx(ss, 1, lane);
;   if (h == 0) rs[r] = rsqrtf(ss / (float)ncol + 1e-6f);
; }
; DEV void qproj_item(const Params& p, int l, int tt, int tf, char* smem, int tid) {
;   const int t0 = tt * 192, f0 = tf * 128;
;   f32x4 acc[2][6];
;   zero_acc<2, 6>(acc);
;   float* rs = (float*)(smem + 122880);
;   __syncthreads();
;   row_scales(p.z + (long)t0 * NINP, C_CQ, 256, rs, tid);
;   gemm_mainloop<2, 6>(p.WuqT + ((long)l * 768 + f0) * 256, 256, p.z + (long)t0 * NINP + C_CQ, NINP, 256, smem, tid, acc);
.LBB0_767:
	s_mul_i32 s6, s15, 43
	s_lshr_b32 s16, s6, 8
	s_mul_i32 s6, s16, 6
	s_sub_i32 s10, s15, s6
	s_cmp_eq_u32 s16, 0
	v_readlane_b32 s8, v255, 42
	s_cselect_b64 s[6:7], -1, 0
	v_readlane_b32 s9, v255, 43
	s_and_b64 s[6:7], s[8:9], s[6:7]
	s_and_b64 vcc, exec, s[6:7]
	s_cbranch_vccnz .LBB0_749
	v_readlane_b32 s6, v255, 10
	s_add_i32 s16, s16, s6
	s_mul_i32 s17, s16, 0xc0
	s_movk_i32 s8, 0x180
	s_mul_i32 s6, s16, 0x330000
	s_mul_hi_i32 s7, s17, 0x4400
	v_cmp_gt_i32_e32 vcc, s8, v58
	s_waitcnt vmcnt(0)
	s_barrier
	v_and_b32_e32 v132, 0xff, v197
	v_lshlrev_b32_e32 v132, 4, v132
	global_load_dwordx4 v[128:131], v132, s[82:83]
	s_and_saveexec_b64 s[8:9], vcc
	s_cbranch_execz .LBB0_773
	v_ashrrev_i32_e32 v2, 1, v58
	v_mov_b64_e32 v[0:1], s[6:7]
	v_mad_i64_i32 v[0:1], s[18:19], v2, s33, v[0:1]
	v_and_b32_e32 v3, 1, v58
	v_lshlrev_b32_e32 v156, 8, v3
	v_readlane_b32 s18, v254, 37
	v_lshl_add_u64 v[0:1], v[0:1], 0, v[156:157]
	v_readlane_b32 s19, v254, 38
	v_mov_b32_e32 v4, 0
	s_mov_b32 s11, -8
	v_lshl_add_u64 v[0:1], s[18:19], 0, v[0:1]

; template <int ROWS>
; DEV void stage_tile(const u16* __restrict__ gbase, long ld, int k0, char* lds, int tid) {
; #pragma unroll
;   for (int i = 0; i < ROWS / 64; ++i) {
;     int idx = i * 512 + tid;
;     int r = idx >> 3, s = idx & 7;
;     int c = s ^ ((r >> 1) & 7);
;     const u16* g = gbase + (long)r * ld + k0 + c * 8;
;     __builtin_amdgcn_global_load_lds((const unsigned*)g, (unsigned*)(lds + idx * 16), 16, 0, 0);
;   }
; }
; template <int WN, int WT>
; DEV void gemm_mainloop(const u16* __restrict__ Wt, long ldw, const u16* __restrict__ A, long lda, int K,
;                        char* smem, int tid, f32x4 (&acc)[WN][WT]) {
;   constexpr int NR = WN * 64, TR = WT * 32;
;   constexpr int WB = NR * 128, STG = (NR + TR) * 128;
;   constexpr int NLD = (NR + TR) / 64;
;   static_assert(3 * STG <= 147456, "LDS stages");
;   const int wid = tid >> 6, lane = tid & 63, fr = lane & 15, fq = lane >> 4, wn = wid & 3, wt = wid >> 2;
;   const int nk = K >> 6;
;   __syncthreads();
;   stage_tile<NR>(Wt, ldw, 0, smem, tid);
;   stage_tile<TR>(A, lda, 0, smem + WB, tid);
;   if (nk > 1) {
;     stage_tile<NR>(Wt, ldw, 64, smem + STG, tid);
;     stage_tile<TR>(A, lda, 64, smem + STG + WB, tid);
;   }
; DEV void qproj_item(const Params& p, int l, int tt, int tf, char* smem, int tid) {
;     ...
;   zero_acc<2, 6>(acc);
.LBB0_773:
	s_or_b64 exec, exec, s[8:9]
	s_waitcnt vmcnt(0)
	v_add_u32_e32 v132, 0x1f000, v132
	ds_write_b128 v132, v[128:131]
	s_lshl_b32 s8, s10, 7
	s_add_u32 s10, s88, s6
	s_addc_u32 s11, s89, s7
	s_ashr_i32 s9, s8, 31
	s_mul_i32 s18, s14, 0x300
	s_add_u32 s18, s8, s18
	s_addc_u32 s19, s9, 0
	v_readlane_b32 s40, v253, 7
	v_lshrrev_b32_e32 v18, 4, v58
	v_ashrrev_i32_e32 v2, 3, v58
	s_lshl_b64 s[18:19], s[18:19], 9
	v_readlane_b32 s46, v253, 13
	s_waitcnt lgkmcnt(0)
	v_xor_b32_e32 v0, v18, v58
	v_ashrrev_i32_e32 v3, 31, v2
	v_readlane_b32 s47, v253, 14
	s_add_u32 s18, s46, s18
	v_lshlrev_b32_e32 v0, 4, v0
	v_lshlrev_b64 v[4:5], 9, v[2:3]
	v_add_u32_e32 v3, 0x200, v58
	s_addc_u32 s19, s47, s19
	v_and_b32_e32 v156, 0x70, v0
	v_lshlrev_b32_e32 v59, 4, v58
	v_ashrrev_i32_e32 v8, 3, v3
	v_lshl_add_u64 v[0:1], s[18:19], 0, v[156:157]
	v_readfirstlane_b32 s18, v59
	v_ashrrev_i32_e32 v9, 31, v8
	v_lshlrev_b32_e32 v60, 4, v3
	v_lshl_add_u64 v[12:13], s[10:11], 0, v[156:157]
	v_lshl_add_u64 v[6:7], v[0:1], 0, v[4:5]
	s_mov_b32 m0, s18
	v_lshlrev_b64 v[10:11], 9, v[8:9]
	v_readfirstlane_b32 s18, v60
	v_mad_i64_i32 v[14:15], s[10:11], v2, s33, v[12:13]
	v_add_u32_e32 v3, 0x4000, v59
	s_barrier
	global_load_lds_dwordx4 v[6:7], off
	v_lshl_add_u64 v[0:1], v[0:1], 0, v[10:11]
	s_mov_b32 m0, s18
	v_readfirstlane_b32 s10, v3
	global_load_lds_dwordx4 v[0:1], off
	s_mov_b32 m0, s10
	v_mad_i64_i32 v[16:17], s[10:11], v8, s33, v[12:13]
	v_add_u32_e32 v3, 0x4000, v60
	global_load_lds_dwordx4 v[14:15], off
	v_readfirstlane_b32 s10, v3
	v_add_u32_e32 v3, 0x400, v58
	v_ashrrev_i32_e32 v9, 3, v3
	v_lshlrev_b32_e32 v61, 4, v3
	s_mov_b32 m0, s10
	v_mad_i64_i32 v[12:13], s[10:11], v9, s33, v[12:13]
	v_add_u32_e32 v3, 0x4000, v61
	global_load_lds_dwordx4 v[16:17], off
	v_readfirstlane_b32 s10, v3
	v_add_u32_e32 v3, 0xa000, v59
	s_mov_b32 m0, s10
	v_readfirstlane_b32 s10, v3
	v_add_u32_e32 v3, 0xa000, v60
	global_load_lds_dwordx4 v[12:13], off
	v_lshl_add_u64 v[6:7], v[6:7], 0, s[34:35]
	s_mov_b32 m0, s10
	v_readfirstlane_b32 s10, v3
	v_add_u32_e32 v3, 0xe000, v59
	global_load_lds_dwordx4 v[6:7], off
	v_lshl_add_u64 v[0:1], v[0:1], 0, s[34:35]
	s_mov_b32 m0, s10
	v_readfirstlane_b32 s10, v3
	v_add_u32_e32 v3, 0xe000, v60
	global_load_lds_dwordx4 v[0:1], off
	v_lshl_add_u64 v[0:1], v[14:15], 0, s[34:35]
	s_mov_b32 m0, s10
	v_readfirstlane_b32 s10, v3
	v_add_u32_e32 v3, 0xe000, v61
	global_load_lds_dwordx4 v[0:1], off
	v_lshl_add_u64 v[0:1], v[16:17], 0, s[34:35]
	s_mov_b32 m0, s10
	v_readfirstlane_b32 s10, v3
	global_load_lds_dwordx4 v[0:1], off
	v_lshl_add_u64 v[0:1], v[12:13], 0, s[34:35]
	s_mov_b32 m0, s10
	v_lshrrev_b32_e32 v63, 1, v58
	global_load_lds_dwordx4 v[0:1], off
	v_lshrrev_b32_e32 v0, 8, v58
	v_and_b32_e32 v1, 15, v58
	v_bfe_u32 v6, v58, 1, 3
	v_mul_i32_i24_e32 v0, 0x60, v0
	v_bfe_u32 v66, v58, 4, 2
	v_and_b32_e32 v64, 0x60, v63
	v_or_b32_e32 v62, v0, v1
	v_bitop3_b32 v0, v18, v6, 3 bitop3:0x6c
	v_or_b32_e32 v3, v64, v1
	v_lshlrev_b32_e32 v65, 4, v0
	v_bitop3_b32 v0, v66, v6, 4 bitop3:0x36
	v_lshlrev_b32_e32 v67, 7, v3
	v_lshlrev_b32_e32 v69, 4, v0
	v_mov_b64_e32 v[0:1], s[6:7]
	v_bitop3_b32 v3, v18, 7, v58 bitop3:0x48
	v_mad_i64_i32 v[6:7], s[6:7], v9, s33, v[0:1]
	v_lshlrev_b32_e32 v156, 4, v3
	v_readlane_b32 s10, v254, 39
	v_lshl_add_u64 v[6:7], v[6:7], 0, v[156:157]
	v_readlane_b32 s11, v254, 40
	v_lshlrev_b32_e32 v68, 7, v62
	s_mov_b32 s18, 0
	v_lshl_add_u64 v[48:49], s[10:11], 0, v[6:7]
	v_mad_i64_i32 v[6:7], s[6:7], v8, s33, v[0:1]
	v_mad_i64_i32 v[0:1], s[6:7], v2, s33, v[0:1]
	v_lshl_add_u64 v[6:7], v[6:7], 0, v[156:157]
	v_lshl_add_u64 v[0:1], v[0:1], 0, v[156:157]
	s_lshl_b64 s[6:7], s[8:9], 9
	v_lshl_add_u64 v[50:51], s[10:11], 0, v[6:7]
	v_lshl_add_u64 v[52:53], s[10:11], 0, v[0:1]
	v_lshl_add_u64 v[0:1], v[10:11], 0, s[6:7]
	v_readlane_b32 s10, v255, 34
	v_or_b32_e32 v0, v0, v156
	v_readlane_b32 s11, v255, 35
	s_mov_b32 s9, 0
	v_readlane_b32 s41, v253, 8
	v_lshl_add_u64 v[54:55], s[10:11], 0, v[0:1]
	v_lshl_add_u64 v[0:1], v[4:5], 0, s[6:7]
	v_or_b32_e32 v0, v0, v156
	v_lshl_add_u64 v[56:57], s[10:11], 0, v[0:1]
	v_mov_b32_e32 v0, 0
	s_mov_b64 s[6:7], 0
	v_mov_b32_e32 v1, v0
	v_mov_b32_e32 v2, v0
	v_mov_b32_e32 v3, v0
	v_mov_b32_e32 v4, v0
	v_mov_b32_e32 v5, v0
	v_mov_b32_e32 v6, v0
	v_mov_b32_e32 v7, v0
	v_mov_b32_e32 v8, v0
	v_mov_b32_e32 v9, v0
	v_mov_b32_e32 v10, v0
	v_mov_b32_e32 v11, v0
	v_mov_b32_e32 v12, v0
	v_mov_b32_e32 v13, v0
	v_mov_b32_e32 v14, v0
	v_mov_b32_e32 v15, v0
	v_mov_b32_e32 v16, v0
	v_mov_b32_e32 v17, v0
	v_mov_b32_e32 v18, v0
	v_mov_b32_e32 v19, v0
	v_mov_b32_e32 v20, v0
	v_mov_b32_e32 v21, v0
	v_mov_b32_e32 v22, v0
	v_mov_b32_e32 v23, v0
	v_mov_b32_e32 v24, v0
	v_mov_b32_e32 v25, v0
	v_mov_b32_e32 v26, v0
	v_mov_b32_e32 v27, v0
	v_mov_b32_e32 v28, v0
	v_mov_b32_e32 v29, v0
	v_mov_b32_e32 v30, v0
	v_mov_b32_e32 v31, v0
	v_mov_b32_e32 v32, v0
	v_mov_b32_e32 v33, v0
	v_mov_b32_e32 v34, v0
	v_mov_b32_e32 v35, v0
	v_mov_b32_e32 v36, v0
	v_mov_b32_e32 v37, v0
	v_mov_b32_e32 v38, v0
	v_mov_b32_e32 v39, v0
	v_mov_b32_e32 v40, v0
	v_mov_b32_e32 v41, v0
	v_mov_b32_e32 v42, v0
	v_mov_b32_e32 v43, v0
	v_mov_b32_e32 v44, v0
	v_mov_b32_e32 v45, v0
	v_mov_b32_e32 v46, v0
	v_mov_b32_e32 v47, v0
	v_readlane_b32 s42, v253, 9
	v_readlane_b32 s43, v253, 10
	v_readlane_b32 s44, v253, 11
	v_readlane_b32 s45, v253, 12
	v_readlane_b32 s48, v253, 15
	v_readlane_b32 s49, v253, 16
	v_readlane_b32 s50, v253, 17
	v_readlane_b32 s51, v253, 18
	v_readlane_b32 s52, v253, 19
	v_readlane_b32 s53, v253, 20
	v_readlane_b32 s54, v253, 21
	v_readlane_b32 s55, v253, 22
	s_branch .LBB0_775

; DEV void qproj_item(const Params& p, int l, int tt, int tf, char* smem, int tid) {
;     ...
;   for (int n = 0; n < 2; ++n) {
;     const int fb = f0 + wn * 32 + n * 16;
;     const int head = fb / 96, part = (fb % 96) >> 4;
;     const int dd = part * 16 + fq * 4;
; #pragma unroll
;     for (int t = 0; t < 6; ++t) {
;       const int tl = wt * 96 + t * 16 + fr;
;       const int j = j0 + tl;
;       const float sc = rs[tl];
;       float v0 = acc[n][t][0] * sc, v1 = acc[n][t][1] * sc, v2 = acc[n][t][2] * sc, v3 = acc[n][t][3] * sc;
;       if (part >= 4) {
;         float p0 = shx(v0, 32, lane), p1 = shx(v1, 32, lane), p2 = shx(v2, 32, lane), p3 = shx(v3, 32, lane);
;         if (j >= NCTX) {
;           const int tq = j - NCTX;
;           const int pos = (part == 4) ? (tq >> 6) : (tq & 63);
;           const float* rp = p.rope + (pos * 8 + (fq & 1) * 4) * 2;
;           float4 cs01 = *(const float4*)rp, cs23 = *(const float4*)(rp + 4);
;           if ((fq >> 1) == 0) {
;             v0 = v0 * cs01.x - p0 * cs01.y; v1 = v1 * cs01.z - p1 * cs01.w;
;             v2 = v2 * cs23.x - p2 * cs23.y; v3 = v3 * cs23.z - p3 * cs23.w;
;           } else {
;             v0 = p0 * cs01.y + v0 * cs01.x; v1 = p1 * cs01.w + v1 * cs01.z;
;             v2 = p2 * cs23.y + v2 * cs23.x; v3 = p3 * cs23.w + v3 * cs23.z;
;           }
;         }
;       }
;       uint2 o;
;       o.x = pack2(v0 * QSCALE, v1 * QSCALE);
;       o.y = pack2(v2 * QSCALE, v3 * QSCALE);
;       *(uint2*)(p.Q + ((long)(bl * 8 + head) * NTOK + j) * 96 + dd) = o;
;       asm volatile("" ::: "memory");
;     }
.LBB0_830:
	s_mul_hi_i32 s6, s17, 0x38e38e39
	s_lshr_b32 s7, s6, 31
	s_ashr_i32 s6, s6, 9
	s_add_i32 s6, s6, s7
	s_mulk_i32 s6, 0x900
	v_and_b32_e32 v48, 63, v58
	s_sub_i32 s17, s17, s6
	v_or_b32_e32 v67, s8, v64
	s_mov_b32 s6, 0x2aaaaaab
	v_lshlrev_b32_e32 v49, 2, v48
	v_cmp_lt_u32_e32 vcc, 31, v48
	v_mul_hi_i32 v48, v67, s6
	v_xor_b32_e32 v64, 0x80, v49
	v_lshrrev_b32_e32 v49, 31, v48
	v_ashrrev_i32_e32 v48, 4, v48
	v_add_u32_e32 v53, v48, v49
	v_mov_b32_e32 v48, 0x1e000
	v_lshl_add_u32 v65, v62, 2, v48
	ds_read_b32 v48, v65
	s_movk_i32 s6, 0x60
	v_mul_lo_u32 v49, v53, s6
	v_sub_u32_e32 v68, v67, v49
	v_and_b32_e32 v63, 8, v63
	v_cmp_lt_i32_e64 s[40:41], 48, v68
	v_cmp_eq_u32_e64 s[38:39], 64, v68
	v_add_u32_e32 v52, s17, v62
	s_waitcnt lgkmcnt(0)
	v_pk_mul_f32 v[56:57], v[44:45], v[48:49] op_sel_hi:[1,0]
	v_pk_mul_f32 v[54:55], v[46:47], v[48:49] op_sel_hi:[1,0]
	s_and_saveexec_b64 s[6:7], s[40:41]
	s_cbranch_execz .LBB0_838
	ds_bpermute_b32 v60, v64, v56
	ds_bpermute_b32 v61, v64, v57
	ds_bpermute_b32 v58, v64, v54
	ds_bpermute_b32 v59, v64, v55
	v_cmp_lt_i32_e64 s[42:43], s67, v52
	s_and_saveexec_b64 s[8:9], s[42:43]
	s_cbranch_execz .LBB0_837
	v_add_u32_e32 v44, 0xffffff00, v52
	v_lshrrev_b32_e32 v44, 6, v44
	v_and_b32_e32 v45, 47, v62
	v_cndmask_b32_e64 v44, v45, v44, s[38:39]
	v_lshlrev_b32_e32 v45, 2, v63
	v_lshl_or_b32 v48, v44, 6, v45
	v_add_u32_e32 v48, 0x1f000, v48
	ds_read_b128 v[44:47], v48 offset:16
	s_nop 0
	ds_read_b128 v[48:51], v48
	s_and_saveexec_b64 s[10:11], vcc
	s_xor_b64 s[10:11], exec, s[10:11]
	s_cbranch_execz .LBB0_834
	s_waitcnt lgkmcnt(0)
	v_mov_b32_e32 v70, v49
	v_mov_b32_e32 v71, v51
	s_waitcnt lgkmcnt(2)
	v_pk_mul_f32 v[60:61], v[70:71], v[60:61]
	v_mov_b32_e32 v49, v50
	v_pk_fma_f32 v[56:57], v[56:57], v[48:49], v[60:61]
	v_mov_b32_e32 v48, v45
	v_mov_b32_e32 v49, v47
	s_waitcnt lgkmcnt(0)
	v_pk_mul_f32 v[48:49], v[48:49], v[58:59]
	v_mov_b32_e32 v45, v46
	v_pk_fma_f32 v[54:55], v[54:55], v[44:45], v[48:49]
.LBB0_834:
	s_andn2_saveexec_b64 s[10:11], s[10:11]
	s_cbranch_execz .LBB0_836
	s_waitcnt lgkmcnt(0)
	v_mov_b32_e32 v71, v50
	v_mov_b32_e32 v50, v49
	v_mov_b32_e32 v70, v48
	s_waitcnt lgkmcnt(2)
	v_pk_mul_f32 v[48:49], v[50:51], v[60:61]
	s_nop 0
	v_pk_fma_f32 v[56:57], v[56:57], v[70:71], v[48:49] neg_lo:[0,0,1] neg_hi:[0,0,1]
	v_mov_b32_e32 v49, v46
	v_mov_b32_e32 v46, v45
	v_mov_b32_e32 v48, v44
	s_waitcnt lgkmcnt(0)
	v_pk_mul_f32 v[44:45], v[46:47], v[58:59]
	s_nop 0
	v_pk_fma_f32 v[54:55], v[54:55], v[48:49], v[44:45] neg_lo:[0,0,1] neg_hi:[0,0,1]

; DEV void qproj_item(const Params& p, int l, int tt, int tf, char* smem, int tid) {
;     ...
;   for (int n = 0; n < 2; ++n) {
;     const int fb = f0 + wn * 32 + n * 16;
;     const int head = fb / 96, part = (fb % 96) >> 4;
;     const int dd = part * 16 + fq * 4;
; #pragma unroll
;     for (int t = 0; t < 6; ++t) {
;       const int tl = wt * 96 + t * 16 + fr;
;       const int j = j0 + tl;
;       const float sc = rs[tl];
;       float v0 = acc[n][t][0] * sc, v1 = acc[n][t][1] * sc, v2 = acc[n][t][2] * sc, v3 = acc[n][t][3] * sc;
;       if (part >= 4) {
;         float p0 = shx(v0, 32, lane), p1 = shx(v1, 32, lane), p2 = shx(v2, 32, lane), p3 = shx(v3, 32, lane);
;         if (j >= NCTX) {
;           const int tq = j - NCTX;
;           const int pos = (part == 4) ? (tq >> 6) : (tq & 63);
;           const float* rp = p.rope + (pos * 8 + (fq & 1) * 4) * 2;
;           float4 cs01 = *(const float4*)rp, cs23 = *(const float4*)(rp + 4);
;           if ((fq >> 1) == 0) {
;             v0 = v0 * cs01.x - p0 * cs01.y; v1 = v1 * cs01.z - p1 * cs01.w;
;             v2 = v2 * cs23.x - p2 * cs23.y; v3 = v3 * cs23.z - p3 * cs23.w;
;           } else {
;             v0 = p0 * cs01.y + v0 * cs01.x; v1 = p1 * cs01.w + v1 * cs01.z;
;             v2 = p2 * cs23.y + v2 * cs23.x; v3 = p3 * cs23.w + v3 * cs23.z;
;           }
;         }
;       }
;       uint2 o;
;       o.x = pack2(v0 * QSCALE, v1 * QSCALE);
;       o.y = pack2(v2 * QSCALE, v3 * QSCALE);
;       *(uint2*)(p.Q + ((long)(bl * 8 + head) * NTOK + j) * 96 + dd) = o;
;       asm volatile("" ::: "memory");
;     }
.LBB0_838:
	s_or_b64 exec, exec, s[6:7]
	s_mul_hi_i32 s6, s16, 0x2aaaaaab
	s_lshr_b32 s7, s6, 31
	s_lshr_b32 s6, s6, 1
	s_add_i32 s6, s6, s7
	s_lshl_b32 s16, s6, 3
	s_mov_b32 s6, 0x3e16c740
	s_waitcnt lgkmcnt(0)
	v_add_u32_e32 v49, s16, v53
	v_pk_mul_f32 v[44:45], v[56:57], s[6:7] op_sel_hi:[1,0]
	v_pk_mul_f32 v[46:47], v[54:55], s[6:7] op_sel_hi:[1,0]
	v_ashrrev_i32_e32 v53, 31, v52
	v_lshlrev_b32_e32 v69, 2, v66
	v_cvt_pk_bf16_f32 v44, v44, v45
	v_cvt_pk_bf16_f32 v45, v46, v47
	v_mad_i64_i32 v[46:47], s[6:7], v49, s66, v[52:53]
	v_mov_b64_e32 v[54:55], s[90:91]
	s_movk_i32 s8, 0xc0
	v_or_b32_e32 v50, v68, v69
	v_mad_u64_u32 v[54:55], s[6:7], v46, s8, v[54:55]
	v_ashrrev_i32_e32 v51, 31, v50
	v_mad_i32_i24 v55, v47, s8, v55
	v_lshl_add_u64 v[46:47], v[50:51], 1, v[54:55]
	global_store_dwordx2 v[46:47], v[44:45], off
	v_or_b32_e32 v66, 16, v62
	v_mov_b32_e32 v44, 0x1e000
	v_lshl_add_u32 v70, v66, 2, v44
	ds_read_b32 v44, v70
	v_add_u32_e32 v48, s17, v66
	s_waitcnt lgkmcnt(0)
	v_pk_mul_f32 v[54:55], v[40:41], v[44:45] op_sel_hi:[1,0]
	v_pk_mul_f32 v[56:57], v[42:43], v[44:45] op_sel_hi:[1,0]
	s_and_saveexec_b64 s[6:7], s[40:41]
	s_cbranch_execz .LBB0_846
	ds_bpermute_b32 v60, v64, v54
	ds_bpermute_b32 v61, v64, v55
	ds_bpermute_b32 v58, v64, v56
	ds_bpermute_b32 v59, v64, v57
	v_cmp_lt_i32_e64 s[42:43], s67, v48
	s_and_saveexec_b64 s[8:9], s[42:43]
	s_cbranch_execz .LBB0_845
	v_add_u32_e32 v40, 0xffffff00, v48
	v_lshrrev_b32_e32 v40, 6, v40
	v_and_b32_e32 v41, 63, v66
	v_cndmask_b32_e64 v40, v41, v40, s[38:39]
	v_lshlrev_b32_e32 v41, 2, v63
	v_lshl_or_b32 v44, v40, 6, v41
	v_add_u32_e32 v44, 0x1f000, v44
	ds_read_b128 v[40:43], v44 offset:16
	s_nop 0
	ds_read_b128 v[44:47], v44
	s_and_saveexec_b64 s[10:11], vcc
	s_xor_b64 s[10:11], exec, s[10:11]
	s_cbranch_execz .LBB0_842
	s_waitcnt lgkmcnt(0)
	v_mov_b32_e32 v72, v45
	v_mov_b32_e32 v73, v47
	s_waitcnt lgkmcnt(2)
	v_pk_mul_f32 v[60:61], v[72:73], v[60:61]
	v_mov_b32_e32 v45, v46
	v_pk_fma_f32 v[54:55], v[54:55], v[44:45], v[60:61]
	v_mov_b32_e32 v44, v41
	v_mov_b32_e32 v45, v43
	s_waitcnt lgkmcnt(0)
	v_pk_mul_f32 v[44:45], v[44:45], v[58:59]
	v_mov_b32_e32 v41, v42
	v_pk_fma_f32 v[56:57], v[56:57], v[40:41], v[44:45]
.LBB0_842:
	s_andn2_saveexec_b64 s[10:11], s[10:11]
	s_cbranch_execz .LBB0_844
	s_waitcnt lgkmcnt(0)
	v_mov_b32_e32 v73, v46
	v_mov_b32_e32 v46, v45
	v_mov_b32_e32 v72, v44
	s_waitcnt lgkmcnt(2)
	v_pk_mul_f32 v[44:45], v[46:47], v[60:61]
	s_nop 0
	v_pk_fma_f32 v[54:55], v[54:55], v[72:73], v[44:45] neg_lo:[0,0,1] neg_hi:[0,0,1]
	v_mov_b32_e32 v45, v42
	v_mov_b32_e32 v42, v41
	v_mov_b32_e32 v44, v40
	s_waitcnt lgkmcnt(0)
	v_pk_mul_f32 v[40:41], v[42:43], v[58:59]
	s_nop 0
	v_pk_fma_f32 v[56:57], v[56:57], v[44:45], v[40:41] neg_lo:[0,0,1] neg_hi:[0,0,1]

; DEV void qproj_item(const Params& p, int l, int tt, int tf, char* smem, int tid) {
;     ...
;   for (int n = 0; n < 2; ++n) {
;     const int fb = f0 + wn * 32 + n * 16;
;     const int head = fb / 96, part = (fb % 96) >> 4;
;     const int dd = part * 16 + fq * 4;
; #pragma unroll
;     for (int t = 0; t < 6; ++t) {
;       const int tl = wt * 96 + t * 16 + fr;
;       const int j = j0 + tl;
;       const float sc = rs[tl];
;       float v0 = acc[n][t][0] * sc, v1 = acc[n][t][1] * sc, v2 = acc[n][t][2] * sc, v3 = acc[n][t][3] * sc;
;       if (part >= 4) {
;         float p0 = shx(v0, 32, lane), p1 = shx(v1, 32, lane), p2 = shx(v2, 32, lane), p3 = shx(v3, 32, lane);
;         if (j >= NCTX) {
;           const int tq = j - NCTX;
;           const int pos = (part == 4) ? (tq >> 6) : (tq & 63);
;           const float* rp = p.rope + (pos * 8 + (fq & 1) * 4) * 2;
;           float4 cs01 = *(const float4*)rp, cs23 = *(const float4*)(rp + 4);
;           if ((fq >> 1) == 0) {
;             v0 = v0 * cs01.x - p0 * cs01.y; v1 = v1 * cs01.z - p1 * cs01.w;
;             v2 = v2 * cs23.x - p2 * cs23.y; v3 = v3 * cs23.z - p3 * cs23.w;
;           } else {
;             v0 = p0 * cs01.y + v0 * cs01.x; v1 = p1 * cs01.w + v1 * cs01.z;
;             v2 = p2 * cs23.y + v2 * cs23.x; v3 = p3 * cs23.w + v3 * cs23.z;
;           }
;         }
;       }
;       uint2 o;
;       o.x = pack2(v0 * QSCALE, v1 * QSCALE);
;       o.y = pack2(v2 * QSCALE, v3 * QSCALE);
;       *(uint2*)(p.Q + ((long)(bl * 8 + head) * NTOK + j) * 96 + dd) = o;
;       asm volatile("" ::: "memory");
;     }
.LBB0_846:
	s_or_b64 exec, exec, s[6:7]
	s_waitcnt lgkmcnt(0)
	v_mad_i64_i32 v[46:47], s[6:7], v49, s66, 0
	s_mov_b32 s6, 0x3e16c740
	s_nop 0
	v_pk_mul_f32 v[40:41], v[54:55], s[6:7] op_sel_hi:[1,0]
	v_pk_mul_f32 v[42:43], v[56:57], s[6:7] op_sel_hi:[1,0]
	v_ashrrev_i32_e32 v49, 31, v48
	v_cvt_pk_bf16_f32 v40, v40, v41
	v_cvt_pk_bf16_f32 v41, v42, v43
	v_lshl_add_u64 v[42:43], v[46:47], 0, v[48:49]
	v_mov_b64_e32 v[44:45], s[90:91]
	s_movk_i32 s8, 0xc0
	v_mad_u64_u32 v[44:45], s[6:7], v42, s8, v[44:45]
	v_mov_b32_e32 v42, v45
	v_mad_u64_u32 v[42:43], s[6:7], v43, s8, v[42:43]
	v_mov_b32_e32 v45, v42
	v_lshl_add_u64 v[42:43], v[50:51], 1, v[44:45]
	global_store_dwordx2 v[42:43], v[40:41], off
	ds_read_b32 v40, v65 offset:128
	v_add_u32_e32 v68, 32, v62
	v_add_u32_e32 v44, s17, v68
	s_waitcnt lgkmcnt(0)
	v_pk_mul_f32 v[54:55], v[36:37], v[40:41] op_sel_hi:[1,0]
	v_pk_mul_f32 v[56:57], v[38:39], v[40:41] op_sel_hi:[1,0]
	s_and_saveexec_b64 s[6:7], s[40:41]
	s_cbranch_execz .LBB0_854
	ds_bpermute_b32 v60, v64, v54
	ds_bpermute_b32 v61, v64, v55
	ds_bpermute_b32 v58, v64, v56
	ds_bpermute_b32 v59, v64, v57
	v_cmp_lt_i32_e64 s[42:43], s67, v44
	s_and_saveexec_b64 s[8:9], s[42:43]
	s_cbranch_execz .LBB0_853
	v_add_u32_e32 v36, 0xffffff00, v44
	v_lshrrev_b32_e32 v36, 6, v36
	v_and_b32_e32 v37, 47, v68
	v_cndmask_b32_e64 v36, v37, v36, s[38:39]
	v_lshlrev_b32_e32 v37, 2, v63
	v_lshl_or_b32 v40, v36, 6, v37
	v_add_u32_e32 v40, 0x1f000, v40
	ds_read_b128 v[36:39], v40 offset:16
	s_nop 0
	ds_read_b128 v[40:43], v40
	s_and_saveexec_b64 s[10:11], vcc
	s_xor_b64 s[10:11], exec, s[10:11]
	s_cbranch_execz .LBB0_850
	s_waitcnt lgkmcnt(0)
	v_mov_b32_e32 v72, v41
	v_mov_b32_e32 v73, v43
	s_waitcnt lgkmcnt(2)
	v_pk_mul_f32 v[60:61], v[72:73], v[60:61]
	v_mov_b32_e32 v41, v42
	v_pk_fma_f32 v[54:55], v[54:55], v[40:41], v[60:61]
	v_mov_b32_e32 v40, v37
	v_mov_b32_e32 v41, v39
	s_waitcnt lgkmcnt(0)
	v_pk_mul_f32 v[40:41], v[40:41], v[58:59]
	v_mov_b32_e32 v37, v38
	v_pk_fma_f32 v[56:57], v[56:57], v[36:37], v[40:41]
.LBB0_850:
	s_andn2_saveexec_b64 s[10:11], s[10:11]
	s_cbranch_execz .LBB0_852
	s_waitcnt lgkmcnt(0)
	v_mov_b32_e32 v73, v42
	v_mov_b32_e32 v42, v41
	v_mov_b32_e32 v72, v40
	s_waitcnt lgkmcnt(2)
	v_pk_mul_f32 v[40:41], v[42:43], v[60:61]
	s_nop 0
	v_pk_fma_f32 v[54:55], v[54:55], v[72:73], v[40:41] neg_lo:[0,0,1] neg_hi:[0,0,1]
	v_mov_b32_e32 v41, v38
	v_mov_b32_e32 v38, v37
	v_mov_b32_e32 v40, v36
	s_waitcnt lgkmcnt(0)
	v_pk_mul_f32 v[36:37], v[38:39], v[58:59]
	s_nop 0
	v_pk_fma_f32 v[56:57], v[56:57], v[40:41], v[36:37] neg_lo:[0,0,1] neg_hi:[0,0,1]

; DEV void qproj_item(const Params& p, int l, int tt, int tf, char* smem, int tid) {
;     ...
;   for (int n = 0; n < 2; ++n) {
;     const int fb = f0 + wn * 32 + n * 16;
;     const int head = fb / 96, part = (fb % 96) >> 4;
;     const int dd = part * 16 + fq * 4;
; #pragma unroll
;     for (int t = 0; t < 6; ++t) {
;       const int tl = wt * 96 + t * 16 + fr;
;       const int j = j0 + tl;
;       const float sc = rs[tl];
;       float v0 = acc[n][t][0] * sc, v1 = acc[n][t][1] * sc, v2 = acc[n][t][2] * sc, v3 = acc[n][t][3] * sc;
;       if (part >= 4) {
;         float p0 = shx(v0, 32, lane), p1 = shx(v1, 32, lane), p2 = shx(v2, 32, lane), p3 = shx(v3, 32, lane);
;         if (j >= NCTX) {
;           const int tq = j - NCTX;
;           const int pos = (part == 4) ? (tq >> 6) : (tq & 63);
;           const float* rp = p.rope + (pos * 8 + (fq & 1) * 4) * 2;
;           float4 cs01 = *(const float4*)rp, cs23 = *(const float4*)(rp + 4);
;           if ((fq >> 1) == 0) {
;             v0 = v0 * cs01.x - p0 * cs01.y; v1 = v1 * cs01.z - p1 * cs01.w;
;             v2 = v2 * cs23.x - p2 * cs23.y; v3 = v3 * cs23.z - p3 * cs23.w;
;           } else {
;             v0 = p0 * cs01.y + v0 * cs01.x; v1 = p1 * cs01.w + v1 * cs01.z;
;             v2 = p2 * cs23.y + v2 * cs23.x; v3 = p3 * cs23.w + v3 * cs23.z;
;           }
;         }
;       }
;       uint2 o;
;       o.x = pack2(v0 * QSCALE, v1 * QSCALE);
;       o.y = pack2(v2 * QSCALE, v3 * QSCALE);
;       *(uint2*)(p.Q + ((long)(bl * 8 + head) * NTOK + j) * 96 + dd) = o;
;       asm volatile("" ::: "memory");
;     }
.LBB0_854:
	s_or_b64 exec, exec, s[6:7]
	s_mov_b32 s6, 0x3e16c740
	s_waitcnt lgkmcnt(0)
	v_pk_mul_f32 v[36:37], v[54:55], s[6:7] op_sel_hi:[1,0]
	v_pk_mul_f32 v[38:39], v[56:57], s[6:7] op_sel_hi:[1,0]
	v_ashrrev_i32_e32 v45, 31, v44
	v_cvt_pk_bf16_f32 v36, v36, v37
	v_cvt_pk_bf16_f32 v37, v38, v39
	v_lshl_add_u64 v[38:39], v[46:47], 0, v[44:45]
	s_waitcnt lgkmcnt(0)
	v_mov_b64_e32 v[40:41], s[90:91]
	s_movk_i32 s8, 0xc0
	v_mad_u64_u32 v[40:41], s[6:7], v38, s8, v[40:41]
	v_mov_b32_e32 v38, v41
	v_mad_u64_u32 v[38:39], s[6:7], v39, s8, v[38:39]
	v_mov_b32_e32 v41, v38
	v_lshl_add_u64 v[38:39], v[50:51], 1, v[40:41]
	global_store_dwordx2 v[38:39], v[36:37], off
	ds_read_b32 v36, v65 offset:192
	s_waitcnt lgkmcnt(4)
	v_add_u32_e32 v60, 48, v62
	v_add_u32_e32 v40, s17, v60
	s_waitcnt lgkmcnt(0)
	v_pk_mul_f32 v[42:43], v[32:33], v[36:37] op_sel_hi:[1,0]
	v_pk_mul_f32 v[54:55], v[34:35], v[36:37] op_sel_hi:[1,0]
	s_and_saveexec_b64 s[6:7], s[40:41]
	s_cbranch_execz .LBB0_862
	ds_bpermute_b32 v58, v64, v42
	ds_bpermute_b32 v59, v64, v43
	ds_bpermute_b32 v56, v64, v54
	ds_bpermute_b32 v57, v64, v55
	v_cmp_lt_i32_e64 s[42:43], s67, v40
	s_and_saveexec_b64 s[8:9], s[42:43]
	s_cbranch_execz .LBB0_861
	v_add_u32_e32 v32, 0xffffff00, v40
	v_lshrrev_b32_e32 v32, 6, v32
	v_and_b32_e32 v33, 63, v60
	v_cndmask_b32_e64 v32, v33, v32, s[38:39]
	v_lshlrev_b32_e32 v33, 2, v63
	v_lshl_or_b32 v36, v32, 6, v33
	v_add_u32_e32 v36, 0x1f000, v36
	ds_read_b128 v[32:35], v36 offset:16
	s_nop 0
	ds_read_b128 v[36:39], v36
	s_and_saveexec_b64 s[10:11], vcc
	s_xor_b64 s[10:11], exec, s[10:11]
	s_cbranch_execz .LBB0_858
	s_waitcnt lgkmcnt(0)
	v_mov_b32_e32 v72, v37
	v_mov_b32_e32 v73, v39
	s_waitcnt lgkmcnt(2)
	v_pk_mul_f32 v[58:59], v[72:73], v[58:59]
	v_mov_b32_e32 v37, v38
	v_pk_fma_f32 v[42:43], v[42:43], v[36:37], v[58:59]
	v_mov_b32_e32 v36, v33
	v_mov_b32_e32 v37, v35
	s_waitcnt lgkmcnt(0)
	v_pk_mul_f32 v[36:37], v[36:37], v[56:57]
	v_mov_b32_e32 v33, v34
	v_pk_fma_f32 v[54:55], v[54:55], v[32:33], v[36:37]
.LBB0_858:
	s_andn2_saveexec_b64 s[10:11], s[10:11]
	s_cbranch_execz .LBB0_860
	s_waitcnt lgkmcnt(0)
	v_mov_b32_e32 v73, v38
	v_mov_b32_e32 v38, v37
	v_mov_b32_e32 v72, v36
	s_waitcnt lgkmcnt(2)
	v_pk_mul_f32 v[36:37], v[38:39], v[58:59]
	s_nop 0
	v_pk_fma_f32 v[42:43], v[42:43], v[72:73], v[36:37] neg_lo:[0,0,1] neg_hi:[0,0,1]
	v_mov_b32_e32 v37, v34
	v_mov_b32_e32 v34, v33
	v_mov_b32_e32 v36, v32
	s_waitcnt lgkmcnt(0)
	v_pk_mul_f32 v[32:33], v[34:35], v[56:57]
	s_nop 0
	v_pk_fma_f32 v[54:55], v[54:55], v[36:37], v[32:33] neg_lo:[0,0,1] neg_hi:[0,0,1]

; DEV void qproj_item(const Params& p, int l, int tt, int tf, char* smem, int tid) {
;     ...
;   for (int n = 0; n < 2; ++n) {
;     const int fb = f0 + wn * 32 + n * 16;
;     const int head = fb / 96, part = (fb % 96) >> 4;
;     const int dd = part * 16 + fq * 4;
; #pragma unroll
;     for (int t = 0; t < 6; ++t) {
;       const int tl = wt * 96 + t * 16 + fr;
;       const int j = j0 + tl;
;       const float sc = rs[tl];
;       float v0 = acc[n][t][0] * sc, v1 = acc[n][t][1] * sc, v2 = acc[n][t][2] * sc, v3 = acc[n][t][3] * sc;
;       if (part >= 4) {
;         float p0 = shx(v0, 32, lane), p1 = shx(v1, 32, lane), p2 = shx(v2, 32, lane), p3 = shx(v3, 32, lane);
;         if (j >= NCTX) {
;           const int tq = j - NCTX;
;           const int pos = (part == 4) ? (tq >> 6) : (tq & 63);
;           const float* rp = p.rope + (pos * 8 + (fq & 1) * 4) * 2;
;           float4 cs01 = *(const float4*)rp, cs23 = *(const float4*)(rp + 4);
;           if ((fq >> 1) == 0) {
;             v0 = v0 * cs01.x - p0 * cs01.y; v1 = v1 * cs01.z - p1 * cs01.w;
;             v2 = v2 * cs23.x - p2 * cs23.y; v3 = v3 * cs23.z - p3 * cs23.w;
;           } else {
;             v0 = p0 * cs01.y + v0 * cs01.x; v1 = p1 * cs01.w + v1 * cs01.z;
;             v2 = p2 * cs23.y + v2 * cs23.x; v3 = p3 * cs23.w + v3 * cs23.z;
;           }
;         }
;       }
;       uint2 o;
;       o.x = pack2(v0 * QSCALE, v1 * QSCALE);
;       o.y = pack2(v2 * QSCALE, v3 * QSCALE);
;       *(uint2*)(p.Q + ((long)(bl * 8 + head) * NTOK + j) * 96 + dd) = o;
;       asm volatile("" ::: "memory");
;     }
.LBB0_862:
	s_or_b64 exec, exec, s[6:7]
	s_mov_b32 s6, 0x3e16c740
	s_waitcnt lgkmcnt(0)
	v_pk_mul_f32 v[32:33], v[42:43], s[6:7] op_sel_hi:[1,0]
	v_pk_mul_f32 v[34:35], v[54:55], s[6:7] op_sel_hi:[1,0]
	v_ashrrev_i32_e32 v41, 31, v40
	v_cvt_pk_bf16_f32 v32, v32, v33
	v_cvt_pk_bf16_f32 v33, v34, v35
	v_lshl_add_u64 v[34:35], v[46:47], 0, v[40:41]
	s_waitcnt lgkmcnt(0)
	v_mov_b64_e32 v[36:37], s[90:91]
	s_movk_i32 s8, 0xc0
	v_mad_u64_u32 v[36:37], s[6:7], v34, s8, v[36:37]
	v_mov_b32_e32 v34, v37
	v_mad_u64_u32 v[34:35], s[6:7], v35, s8, v[34:35]
	v_mov_b32_e32 v37, v34
	v_lshl_add_u64 v[34:35], v[50:51], 1, v[36:37]
	global_store_dwordx2 v[34:35], v[32:33], off
	ds_read_b32 v32, v65 offset:256
	v_add3_u32 v36, v62, s17, 64
	s_waitcnt lgkmcnt(0)
	v_pk_mul_f32 v[38:39], v[28:29], v[32:33] op_sel_hi:[1,0]
	v_pk_mul_f32 v[42:43], v[30:31], v[32:33] op_sel_hi:[1,0]
	s_and_saveexec_b64 s[6:7], s[40:41]
	s_cbranch_execz .LBB0_870
	ds_bpermute_b32 v56, v64, v38
	ds_bpermute_b32 v57, v64, v39
	ds_bpermute_b32 v54, v64, v42
	ds_bpermute_b32 v55, v64, v43
	v_cmp_lt_i32_e64 s[42:43], s67, v36
	s_and_saveexec_b64 s[8:9], s[42:43]
	s_cbranch_execz .LBB0_869
	v_add_u32_e32 v28, 0xffffff00, v36
	v_lshrrev_b32_e32 v28, 6, v28
	v_and_b32_e32 v29, 47, v62
	v_cndmask_b32_e64 v28, v29, v28, s[38:39]
	v_lshlrev_b32_e32 v29, 2, v63
	v_lshl_or_b32 v32, v28, 6, v29
	v_add_u32_e32 v32, 0x1f000, v32
	ds_read_b128 v[28:31], v32 offset:16
	s_nop 0
	ds_read_b128 v[32:35], v32
	s_and_saveexec_b64 s[10:11], vcc
	s_xor_b64 s[10:11], exec, s[10:11]
	s_cbranch_execz .LBB0_866
	s_waitcnt lgkmcnt(0)
	v_mov_b32_e32 v58, v33
	v_mov_b32_e32 v59, v35
	s_waitcnt lgkmcnt(2)
	v_pk_mul_f32 v[56:57], v[58:59], v[56:57]
	v_mov_b32_e32 v33, v34
	v_pk_fma_f32 v[38:39], v[38:39], v[32:33], v[56:57]
	v_mov_b32_e32 v32, v29
	v_mov_b32_e32 v33, v31
	s_waitcnt lgkmcnt(0)
	v_pk_mul_f32 v[32:33], v[32:33], v[54:55]
	v_mov_b32_e32 v29, v30
	v_pk_fma_f32 v[42:43], v[42:43], v[28:29], v[32:33]
.LBB0_866:
	s_andn2_saveexec_b64 s[10:11], s[10:11]
	s_cbranch_execz .LBB0_868
	s_waitcnt lgkmcnt(0)
	v_mov_b32_e32 v59, v34
	v_mov_b32_e32 v34, v33
	v_mov_b32_e32 v58, v32
	s_waitcnt lgkmcnt(2)
	v_pk_mul_f32 v[32:33], v[34:35], v[56:57]
	s_nop 0
	v_pk_fma_f32 v[38:39], v[38:39], v[58:59], v[32:33] neg_lo:[0,0,1] neg_hi:[0,0,1]
	v_mov_b32_e32 v33, v30
	v_mov_b32_e32 v30, v29
	v_mov_b32_e32 v32, v28
	s_waitcnt lgkmcnt(0)
	v_pk_mul_f32 v[28:29], v[30:31], v[54:55]
	s_nop 0
	v_pk_fma_f32 v[42:43], v[42:43], v[32:33], v[28:29] neg_lo:[0,0,1] neg_hi:[0,0,1]

; DEV void qproj_item(const Params& p, int l, int tt, int tf, char* smem, int tid) {
;     ...
;   for (int n = 0; n < 2; ++n) {
;     const int fb = f0 + wn * 32 + n * 16;
;     const int head = fb / 96, part = (fb % 96) >> 4;
;     const int dd = part * 16 + fq * 4;
; #pragma unroll
;     for (int t = 0; t < 6; ++t) {
;       const int tl = wt * 96 + t * 16 + fr;
;       const int j = j0 + tl;
;       const float sc = rs[tl];
;       float v0 = acc[n][t][0] * sc, v1 = acc[n][t][1] * sc, v2 = acc[n][t][2] * sc, v3 = acc[n][t][3] * sc;
;       if (part >= 4) {
;         float p0 = shx(v0, 32, lane), p1 = shx(v1, 32, lane), p2 = shx(v2, 32, lane), p3 = shx(v3, 32, lane);
;         if (j >= NCTX) {
;           const int tq = j - NCTX;
;           const int pos = (part == 4) ? (tq >> 6) : (tq & 63);
;           const float* rp = p.rope + (pos * 8 + (fq & 1) * 4) * 2;
;           float4 cs01 = *(const float4*)rp, cs23 = *(const float4*)(rp + 4);
;           if ((fq >> 1) == 0) {
;             v0 = v0 * cs01.x - p0 * cs01.y; v1 = v1 * cs01.z - p1 * cs01.w;
;             v2 = v2 * cs23.x - p2 * cs23.y; v3 = v3 * cs23.z - p3 * cs23.w;
;           } else {
;             v0 = p0 * cs01.y + v0 * cs01.x; v1 = p1 * cs01.w + v1 * cs01.z;
;             v2 = p2 * cs23.y + v2 * cs23.x; v3 = p3 * cs23.w + v3 * cs23.z;
;           }
;         }
;       }
;       uint2 o;
;       o.x = pack2(v0 * QSCALE, v1 * QSCALE);
;       o.y = pack2(v2 * QSCALE, v3 * QSCALE);
;       *(uint2*)(p.Q + ((long)(bl * 8 + head) * NTOK + j) * 96 + dd) = o;
;       asm volatile("" ::: "memory");
;     }
.LBB0_870:
	s_or_b64 exec, exec, s[6:7]
	s_mov_b32 s6, 0x3e16c740
	s_waitcnt lgkmcnt(0)
	v_pk_mul_f32 v[28:29], v[38:39], s[6:7] op_sel_hi:[1,0]
	v_pk_mul_f32 v[30:31], v[42:43], s[6:7] op_sel_hi:[1,0]
	v_ashrrev_i32_e32 v37, 31, v36
	v_cvt_pk_bf16_f32 v28, v28, v29
	v_cvt_pk_bf16_f32 v29, v30, v31
	v_lshl_add_u64 v[30:31], v[46:47], 0, v[36:37]
	s_waitcnt lgkmcnt(0)
	v_mov_b64_e32 v[32:33], s[90:91]
	s_movk_i32 s8, 0xc0
	v_mad_u64_u32 v[32:33], s[6:7], v30, s8, v[32:33]
	v_mov_b32_e32 v30, v33
	v_mad_u64_u32 v[30:31], s[6:7], v31, s8, v[30:31]
	v_mov_b32_e32 v33, v30
	v_lshl_add_u64 v[30:31], v[50:51], 1, v[32:33]
	global_store_dwordx2 v[30:31], v[28:29], off
	ds_read_b32 v28, v65 offset:320
	s_waitcnt lgkmcnt(4)
	v_add_u32_e32 v56, 0x50, v62
	v_add_u32_e32 v32, s17, v56
	s_waitcnt lgkmcnt(0)
	v_pk_mul_f32 v[34:35], v[24:25], v[28:29] op_sel_hi:[1,0]
	v_pk_mul_f32 v[38:39], v[26:27], v[28:29] op_sel_hi:[1,0]
	s_and_saveexec_b64 s[6:7], s[40:41]
	s_cbranch_execz .LBB0_878
	ds_bpermute_b32 v54, v64, v34
	ds_bpermute_b32 v55, v64, v35
	ds_bpermute_b32 v42, v64, v38
	ds_bpermute_b32 v43, v64, v39
	v_cmp_lt_i32_e64 s[40:41], s67, v32
	s_and_saveexec_b64 s[8:9], s[40:41]
	s_cbranch_execz .LBB0_877
	v_add_u32_e32 v24, 0xffffff00, v32
	v_lshrrev_b32_e32 v24, 6, v24
	v_and_b32_e32 v25, 63, v56
	v_cndmask_b32_e64 v24, v25, v24, s[38:39]
	v_lshlrev_b32_e32 v25, 2, v63
	v_lshl_or_b32 v28, v24, 6, v25
	v_add_u32_e32 v28, 0x1f000, v28
	ds_read_b128 v[24:27], v28 offset:16
	s_nop 0
	ds_read_b128 v[28:31], v28
	s_and_saveexec_b64 s[10:11], vcc
	s_xor_b64 s[10:11], exec, s[10:11]
	s_cbranch_execz .LBB0_874
	s_waitcnt lgkmcnt(0)
	v_mov_b32_e32 v58, v29
	v_mov_b32_e32 v59, v31
	s_waitcnt lgkmcnt(2)
	v_pk_mul_f32 v[54:55], v[58:59], v[54:55]
	v_mov_b32_e32 v29, v30
	v_pk_fma_f32 v[34:35], v[34:35], v[28:29], v[54:55]
	v_mov_b32_e32 v28, v25
	v_mov_b32_e32 v29, v27
	s_waitcnt lgkmcnt(0)
	v_pk_mul_f32 v[28:29], v[28:29], v[42:43]
	v_mov_b32_e32 v25, v26
	v_pk_fma_f32 v[38:39], v[38:39], v[24:25], v[28:29]
.LBB0_874:
	s_andn2_saveexec_b64 s[10:11], s[10:11]
	s_cbranch_execz .LBB0_876
	s_waitcnt lgkmcnt(0)
	v_mov_b32_e32 v59, v30
	v_mov_b32_e32 v30, v29
	v_mov_b32_e32 v58, v28
	s_waitcnt lgkmcnt(2)
	v_pk_mul_f32 v[28:29], v[30:31], v[54:55]
	s_nop 0
	v_pk_fma_f32 v[34:35], v[34:35], v[58:59], v[28:29] neg_lo:[0,0,1] neg_hi:[0,0,1]
	v_mov_b32_e32 v29, v26
	v_mov_b32_e32 v26, v25
	v_mov_b32_e32 v28, v24
	s_waitcnt lgkmcnt(0)
	v_pk_mul_f32 v[24:25], v[26:27], v[42:43]
	s_nop 0
	v_pk_fma_f32 v[38:39], v[38:39], v[28:29], v[24:25] neg_lo:[0,0,1] neg_hi:[0,0,1]

; DEV void qproj_item(const Params& p, int l, int tt, int tf, char* smem, int tid) {
;     ...
;   for (int n = 0; n < 2; ++n) {
;     const int fb = f0 + wn * 32 + n * 16;
;     const int head = fb / 96, part = (fb % 96) >> 4;
;     const int dd = part * 16 + fq * 4;
; #pragma unroll
;     for (int t = 0; t < 6; ++t) {
;       const int tl = wt * 96 + t * 16 + fr;
;       const int j = j0 + tl;
;       const float sc = rs[tl];
;       float v0 = acc[n][t][0] * sc, v1 = acc[n][t][1] * sc, v2 = acc[n][t][2] * sc, v3 = acc[n][t][3] * sc;
;       if (part >= 4) {
;         float p0 = shx(v0, 32, lane), p1 = shx(v1, 32, lane), p2 = shx(v2, 32, lane), p3 = shx(v3, 32, lane);
;         if (j >= NCTX) {
;           const int tq = j - NCTX;
;           const int pos = (part == 4) ? (tq >> 6) : (tq & 63);
;           const float* rp = p.rope + (pos * 8 + (fq & 1) * 4) * 2;
;           float4 cs01 = *(const float4*)rp, cs23 = *(const float4*)(rp + 4);
;           if ((fq >> 1) == 0) {
;             v0 = v0 * cs01.x - p0 * cs01.y; v1 = v1 * cs01.z - p1 * cs01.w;
;             v2 = v2 * cs23.x - p2 * cs23.y; v3 = v3 * cs23.z - p3 * cs23.w;
;           } else {
;             v0 = p0 * cs01.y + v0 * cs01.x; v1 = p1 * cs01.w + v1 * cs01.z;
;             v2 = p2 * cs23.y + v2 * cs23.x; v3 = p3 * cs23.w + v3 * cs23.z;
;           }
;         }
;       }
;       uint2 o;
;       o.x = pack2(v0 * QSCALE, v1 * QSCALE);
;       o.y = pack2(v2 * QSCALE, v3 * QSCALE);
;       *(uint2*)(p.Q + ((long)(bl * 8 + head) * NTOK + j) * 96 + dd) = o;
;       asm volatile("" ::: "memory");
;     }
.LBB0_878:
	s_or_b64 exec, exec, s[6:7]
	s_mov_b32 s6, 0x3e16c740
	s_waitcnt lgkmcnt(0)
	v_pk_mul_f32 v[24:25], v[34:35], s[6:7] op_sel_hi:[1,0]
	v_pk_mul_f32 v[26:27], v[38:39], s[6:7] op_sel_hi:[1,0]
	v_ashrrev_i32_e32 v33, 31, v32
	v_cvt_pk_bf16_f32 v24, v24, v25
	v_cvt_pk_bf16_f32 v25, v26, v27
	v_lshl_add_u64 v[26:27], v[46:47], 0, v[32:33]
	s_waitcnt lgkmcnt(0)
	v_mov_b64_e32 v[28:29], s[90:91]
	s_movk_i32 s8, 0xc0
	v_mad_u64_u32 v[28:29], s[6:7], v26, s8, v[28:29]
	v_mov_b32_e32 v26, v29
	v_mad_u64_u32 v[26:27], s[6:7], v27, s8, v[26:27]
	v_mov_b32_e32 v29, v26
	v_lshl_add_u64 v[26:27], v[50:51], 1, v[28:29]
	global_store_dwordx2 v[26:27], v[24:25], off
	v_or_b32_e32 v25, 16, v67
	s_mov_b32 s6, 0x2aaaaaab
	v_mul_hi_i32 v24, v25, s6
	v_lshrrev_b32_e32 v26, 31, v24
	v_ashrrev_i32_e32 v27, 4, v24
	ds_read_b32 v24, v65
	s_waitcnt lgkmcnt(2)
	v_add_u32_e32 v42, v27, v26
	s_movk_i32 s6, 0x60
	v_mul_lo_u32 v26, v42, s6
	s_waitcnt lgkmcnt(1)
	v_sub_u32_e32 v43, v25, v26
	v_cmp_lt_i32_e64 s[38:39], 48, v43
	s_waitcnt lgkmcnt(0)
	v_pk_mul_f32 v[28:29], v[20:21], v[24:25] op_sel_hi:[1,0]
	v_pk_mul_f32 v[30:31], v[22:23], v[24:25] op_sel_hi:[1,0]
	s_and_saveexec_b64 s[6:7], s[38:39]
	s_cbranch_execz .LBB0_886
	ds_bpermute_b32 v38, v64, v28
	ds_bpermute_b32 v39, v64, v29
	ds_bpermute_b32 v34, v64, v30
	ds_bpermute_b32 v35, v64, v31
	v_cmp_lt_i32_e64 s[40:41], s67, v52
	s_and_saveexec_b64 s[8:9], s[40:41]
	s_cbranch_execz .LBB0_885
	v_lshlrev_b32_e32 v20, 4, v62
	s_movk_i32 s10, 0x2f0
	v_and_or_b32 v20, v20, s10, v63
	v_lshlrev_b32_e32 v24, 2, v20
	v_add_u32_e32 v24, 0x1f000, v24
	ds_read_b128 v[20:23], v24 offset:16
	s_nop 0
	ds_read_b128 v[24:27], v24
	s_and_saveexec_b64 s[10:11], vcc
	s_xor_b64 s[10:11], exec, s[10:11]
	s_cbranch_execz .LBB0_882
	s_waitcnt lgkmcnt(0)
	v_mov_b32_e32 v46, v25
	v_mov_b32_e32 v47, v27
	s_waitcnt lgkmcnt(2)
	v_pk_mul_f32 v[38:39], v[46:47], v[38:39]
	v_mov_b32_e32 v25, v26
	v_pk_fma_f32 v[28:29], v[28:29], v[24:25], v[38:39]
	v_mov_b32_e32 v24, v21
	v_mov_b32_e32 v25, v23
	s_waitcnt lgkmcnt(0)
	v_pk_mul_f32 v[24:25], v[24:25], v[34:35]
	v_mov_b32_e32 v21, v22
	v_pk_fma_f32 v[30:31], v[30:31], v[20:21], v[24:25]
.LBB0_882:
	s_andn2_saveexec_b64 s[10:11], s[10:11]
	s_cbranch_execz .LBB0_884
	s_waitcnt lgkmcnt(0)
	v_mov_b32_e32 v47, v26
	v_mov_b32_e32 v26, v25
	v_mov_b32_e32 v46, v24
	s_waitcnt lgkmcnt(2)
	v_pk_mul_f32 v[24:25], v[26:27], v[38:39]
	s_nop 0
	v_pk_fma_f32 v[28:29], v[28:29], v[46:47], v[24:25] neg_lo:[0,0,1] neg_hi:[0,0,1]
	v_mov_b32_e32 v25, v22
	v_mov_b32_e32 v22, v21
	v_mov_b32_e32 v24, v20
	s_waitcnt lgkmcnt(0)
	v_pk_mul_f32 v[20:21], v[22:23], v[34:35]
	s_nop 0
	v_pk_fma_f32 v[30:31], v[30:31], v[24:25], v[20:21] neg_lo:[0,0,1] neg_hi:[0,0,1]

; DEV void qproj_item(const Params& p, int l, int tt, int tf, char* smem, int tid) {
;     ...
;   for (int n = 0; n < 2; ++n) {
;     const int fb = f0 + wn * 32 + n * 16;
;     const int head = fb / 96, part = (fb % 96) >> 4;
;     const int dd = part * 16 + fq * 4;
; #pragma unroll
;     for (int t = 0; t < 6; ++t) {
;       const int tl = wt * 96 + t * 16 + fr;
;       const int j = j0 + tl;
;       const float sc = rs[tl];
;       float v0 = acc[n][t][0] * sc, v1 = acc[n][t][1] * sc, v2 = acc[n][t][2] * sc, v3 = acc[n][t][3] * sc;
;       if (part >= 4) {
;         float p0 = shx(v0, 32, lane), p1 = shx(v1, 32, lane), p2 = shx(v2, 32, lane), p3 = shx(v3, 32, lane);
;         if (j >= NCTX) {
;           const int tq = j - NCTX;
;           const int pos = (part == 4) ? (tq >> 6) : (tq & 63);
;           const float* rp = p.rope + (pos * 8 + (fq & 1) * 4) * 2;
;           float4 cs01 = *(const float4*)rp, cs23 = *(const float4*)(rp + 4);
;           if ((fq >> 1) == 0) {
;             v0 = v0 * cs01.x - p0 * cs01.y; v1 = v1 * cs01.z - p1 * cs01.w;
;             v2 = v2 * cs23.x - p2 * cs23.y; v3 = v3 * cs23.z - p3 * cs23.w;
;           } else {
;             v0 = p0 * cs01.y + v0 * cs01.x; v1 = p1 * cs01.w + v1 * cs01.z;
;             v2 = p2 * cs23.y + v2 * cs23.x; v3 = p3 * cs23.w + v3 * cs23.z;
;           }
;         }
;       }
;       uint2 o;
;       o.x = pack2(v0 * QSCALE, v1 * QSCALE);
;       o.y = pack2(v2 * QSCALE, v3 * QSCALE);
;       *(uint2*)(p.Q + ((long)(bl * 8 + head) * NTOK + j) * 96 + dd) = o;
;       asm volatile("" ::: "memory");
;     }
.LBB0_886:
	s_or_b64 exec, exec, s[6:7]
	s_mov_b32 s6, 0x3e16c740
	s_waitcnt lgkmcnt(3)
	v_add_u32_e32 v38, s16, v42
	s_waitcnt lgkmcnt(0)
	v_pk_mul_f32 v[20:21], v[28:29], s[6:7] op_sel_hi:[1,0]
	v_pk_mul_f32 v[22:23], v[30:31], s[6:7] op_sel_hi:[1,0]
	v_cvt_pk_bf16_f32 v20, v20, v21
	v_cvt_pk_bf16_f32 v21, v22, v23
	v_mad_i64_i32 v[22:23], s[6:7], v38, s66, v[52:53]
	s_waitcnt lgkmcnt(0)
	v_mov_b64_e32 v[26:27], s[90:91]
	s_movk_i32 s8, 0xc0
	v_or_b32_e32 v24, v43, v69
	v_mad_u64_u32 v[26:27], s[6:7], v22, s8, v[26:27]
	v_ashrrev_i32_e32 v25, 31, v24
	v_mad_i32_i24 v27, v23, s8, v27
	v_lshl_add_u64 v[22:23], v[24:25], 1, v[26:27]
	global_store_dwordx2 v[22:23], v[20:21], off
	ds_read_b32 v20, v70
	s_waitcnt lgkmcnt(0)
	v_pk_mul_f32 v[26:27], v[16:17], v[20:21] op_sel_hi:[1,0]
	v_pk_mul_f32 v[28:29], v[18:19], v[20:21] op_sel_hi:[1,0]
	s_and_saveexec_b64 s[6:7], s[38:39]
	s_cbranch_execz .LBB0_894
	ds_bpermute_b32 v34, v64, v26
	ds_bpermute_b32 v35, v64, v27
	ds_bpermute_b32 v30, v64, v28
	ds_bpermute_b32 v31, v64, v29
	v_cmp_lt_i32_e64 s[40:41], s67, v48
	s_and_saveexec_b64 s[8:9], s[40:41]
	s_cbranch_execz .LBB0_893
	v_lshlrev_b32_e32 v16, 4, v66
	s_movk_i32 s10, 0x3f0
	v_and_or_b32 v16, v16, s10, v63
	v_lshlrev_b32_e32 v20, 2, v16
	v_add_u32_e32 v20, 0x1f000, v20
	ds_read_b128 v[16:19], v20 offset:16
	s_nop 0
	ds_read_b128 v[20:23], v20
	s_and_saveexec_b64 s[10:11], vcc
	s_xor_b64 s[10:11], exec, s[10:11]
	s_cbranch_execz .LBB0_890
	s_waitcnt lgkmcnt(0)
	v_mov_b32_e32 v42, v21
	v_mov_b32_e32 v43, v23
	s_waitcnt lgkmcnt(2)
	v_pk_mul_f32 v[34:35], v[42:43], v[34:35]
	v_mov_b32_e32 v21, v22
	v_pk_fma_f32 v[26:27], v[26:27], v[20:21], v[34:35]
	v_mov_b32_e32 v20, v17
	v_mov_b32_e32 v21, v19
	s_waitcnt lgkmcnt(0)
	v_pk_mul_f32 v[20:21], v[20:21], v[30:31]
	v_mov_b32_e32 v17, v18
	v_pk_fma_f32 v[28:29], v[28:29], v[16:17], v[20:21]
.LBB0_890:
	s_andn2_saveexec_b64 s[10:11], s[10:11]
	s_cbranch_execz .LBB0_892
	s_waitcnt lgkmcnt(0)
	v_mov_b32_e32 v43, v22
	v_mov_b32_e32 v22, v21
	v_mov_b32_e32 v42, v20
	s_waitcnt lgkmcnt(2)
	v_pk_mul_f32 v[20:21], v[22:23], v[34:35]
	s_nop 0
	v_pk_fma_f32 v[26:27], v[26:27], v[42:43], v[20:21] neg_lo:[0,0,1] neg_hi:[0,0,1]
	v_mov_b32_e32 v21, v18
	v_mov_b32_e32 v18, v17
	v_mov_b32_e32 v20, v16
	s_waitcnt lgkmcnt(0)
	v_pk_mul_f32 v[16:17], v[18:19], v[30:31]
	s_nop 0
	v_pk_fma_f32 v[28:29], v[28:29], v[20:21], v[16:17] neg_lo:[0,0,1] neg_hi:[0,0,1]

; DEV void qproj_item(const Params& p, int l, int tt, int tf, char* smem, int tid) {
;     ...
;   for (int n = 0; n < 2; ++n) {
;     const int fb = f0 + wn * 32 + n * 16;
;     const int head = fb / 96, part = (fb % 96) >> 4;
;     const int dd = part * 16 + fq * 4;
; #pragma unroll
;     for (int t = 0; t < 6; ++t) {
;       const int tl = wt * 96 + t * 16 + fr;
;       const int j = j0 + tl;
;       const float sc = rs[tl];
;       float v0 = acc[n][t][0] * sc, v1 = acc[n][t][1] * sc, v2 = acc[n][t][2] * sc, v3 = acc[n][t][3] * sc;
;       if (part >= 4) {
;         float p0 = shx(v0, 32, lane), p1 = shx(v1, 32, lane), p2 = shx(v2, 32, lane), p3 = shx(v3, 32, lane);
;         if (j >= NCTX) {
;           const int tq = j - NCTX;
;           const int pos = (part == 4) ? (tq >> 6) : (tq & 63);
;           const float* rp = p.rope + (pos * 8 + (fq & 1) * 4) * 2;
;           float4 cs01 = *(const float4*)rp, cs23 = *(const float4*)(rp + 4);
;           if ((fq >> 1) == 0) {
;             v0 = v0 * cs01.x - p0 * cs01.y; v1 = v1 * cs01.z - p1 * cs01.w;
;             v2 = v2 * cs23.x - p2 * cs23.y; v3 = v3 * cs23.z - p3 * cs23.w;
;           } else {
;             v0 = p0 * cs01.y + v0 * cs01.x; v1 = p1 * cs01.w + v1 * cs01.z;
;             v2 = p2 * cs23.y + v2 * cs23.x; v3 = p3 * cs23.w + v3 * cs23.z;
;           }
;         }
;       }
;       uint2 o;
;       o.x = pack2(v0 * QSCALE, v1 * QSCALE);
;       o.y = pack2(v2 * QSCALE, v3 * QSCALE);
;       *(uint2*)(p.Q + ((long)(bl * 8 + head) * NTOK + j) * 96 + dd) = o;
;       asm volatile("" ::: "memory");
;     }
.LBB0_894:
	s_or_b64 exec, exec, s[6:7]
	s_waitcnt lgkmcnt(0)
	v_mad_i64_i32 v[20:21], s[6:7], v38, s66, 0
	s_mov_b32 s6, 0x3e16c740
	s_nop 0
	v_pk_mul_f32 v[16:17], v[26:27], s[6:7] op_sel_hi:[1,0]
	v_pk_mul_f32 v[18:19], v[28:29], s[6:7] op_sel_hi:[1,0]
	v_cvt_pk_bf16_f32 v16, v16, v17
	v_cvt_pk_bf16_f32 v17, v18, v19
	v_lshl_add_u64 v[18:19], v[20:21], 0, v[48:49]
	v_mov_b64_e32 v[22:23], s[90:91]
	s_movk_i32 s8, 0xc0
	v_mad_u64_u32 v[22:23], s[6:7], v18, s8, v[22:23]
	v_mov_b32_e32 v18, v23
	v_mad_u64_u32 v[18:19], s[6:7], v19, s8, v[18:19]
	v_mov_b32_e32 v23, v18
	v_lshl_add_u64 v[18:19], v[24:25], 1, v[22:23]
	global_store_dwordx2 v[18:19], v[16:17], off
	ds_read_b32 v16, v65 offset:128
	s_waitcnt lgkmcnt(0)
	v_pk_mul_f32 v[22:23], v[12:13], v[16:17] op_sel_hi:[1,0]
	v_pk_mul_f32 v[26:27], v[14:15], v[16:17] op_sel_hi:[1,0]
	s_and_saveexec_b64 s[6:7], s[38:39]
	s_cbranch_execz .LBB0_902
	ds_bpermute_b32 v30, v64, v22
	ds_bpermute_b32 v31, v64, v23
	ds_bpermute_b32 v28, v64, v26
	ds_bpermute_b32 v29, v64, v27
	v_cmp_lt_i32_e64 s[40:41], s67, v44
	s_and_saveexec_b64 s[8:9], s[40:41]
	s_cbranch_execz .LBB0_901
	v_lshlrev_b32_e32 v12, 4, v68
	s_movk_i32 s10, 0x2f0
	v_and_or_b32 v12, v12, s10, v63
	v_lshlrev_b32_e32 v16, 2, v12
	v_add_u32_e32 v16, 0x1f000, v16
	ds_read_b128 v[12:15], v16 offset:16
	s_nop 0
	ds_read_b128 v[16:19], v16
	s_and_saveexec_b64 s[10:11], vcc
	s_xor_b64 s[10:11], exec, s[10:11]
	s_cbranch_execz .LBB0_898
	s_waitcnt lgkmcnt(0)
	v_mov_b32_e32 v34, v17
	v_mov_b32_e32 v35, v19
	s_waitcnt lgkmcnt(2)
	v_pk_mul_f32 v[30:31], v[34:35], v[30:31]
	v_mov_b32_e32 v17, v18
	v_pk_fma_f32 v[22:23], v[22:23], v[16:17], v[30:31]
	v_mov_b32_e32 v16, v13
	v_mov_b32_e32 v17, v15
	s_waitcnt lgkmcnt(0)
	v_pk_mul_f32 v[16:17], v[16:17], v[28:29]
	v_mov_b32_e32 v13, v14
	v_pk_fma_f32 v[26:27], v[26:27], v[12:13], v[16:17]
.LBB0_898:
	s_andn2_saveexec_b64 s[10:11], s[10:11]
	s_cbranch_execz .LBB0_900
	s_waitcnt lgkmcnt(0)
	v_mov_b32_e32 v35, v18
	v_mov_b32_e32 v18, v17
	v_mov_b32_e32 v34, v16
	s_waitcnt lgkmcnt(2)
	v_pk_mul_f32 v[16:17], v[18:19], v[30:31]
	s_nop 0
	v_pk_fma_f32 v[22:23], v[22:23], v[34:35], v[16:17] neg_lo:[0,0,1] neg_hi:[0,0,1]
	v_mov_b32_e32 v17, v14
	v_mov_b32_e32 v14, v13
	v_mov_b32_e32 v16, v12
	s_waitcnt lgkmcnt(0)
	v_pk_mul_f32 v[12:13], v[14:15], v[28:29]
	s_nop 0
	v_pk_fma_f32 v[26:27], v[26:27], v[16:17], v[12:13] neg_lo:[0,0,1] neg_hi:[0,0,1]

; DEV void qproj_item(const Params& p, int l, int tt, int tf, char* smem, int tid) {
;     ...
;   for (int n = 0; n < 2; ++n) {
;     const int fb = f0 + wn * 32 + n * 16;
;     const int head = fb / 96, part = (fb % 96) >> 4;
;     const int dd = part * 16 + fq * 4;
; #pragma unroll
;     for (int t = 0; t < 6; ++t) {
;       const int tl = wt * 96 + t * 16 + fr;
;       const int j = j0 + tl;
;       const float sc = rs[tl];
;       float v0 = acc[n][t][0] * sc, v1 = acc[n][t][1] * sc, v2 = acc[n][t][2] * sc, v3 = acc[n][t][3] * sc;
;       if (part >= 4) {
;         float p0 = shx(v0, 32, lane), p1 = shx(v1, 32, lane), p2 = shx(v2, 32, lane), p3 = shx(v3, 32, lane);
;         if (j >= NCTX) {
;           const int tq = j - NCTX;
;           const int pos = (part == 4) ? (tq >> 6) : (tq & 63);
;           const float* rp = p.rope + (pos * 8 + (fq & 1) * 4) * 2;
;           float4 cs01 = *(const float4*)rp, cs23 = *(const float4*)(rp + 4);
;           if ((fq >> 1) == 0) {
;             v0 = v0 * cs01.x - p0 * cs01.y; v1 = v1 * cs01.z - p1 * cs01.w;
;             v2 = v2 * cs23.x - p2 * cs23.y; v3 = v3 * cs23.z - p3 * cs23.w;
;           } else {
;             v0 = p0 * cs01.y + v0 * cs01.x; v1 = p1 * cs01.w + v1 * cs01.z;
;             v2 = p2 * cs23.y + v2 * cs23.x; v3 = p3 * cs23.w + v3 * cs23.z;
;           }
;         }
;       }
;       uint2 o;
;       o.x = pack2(v0 * QSCALE, v1 * QSCALE);
;       o.y = pack2(v2 * QSCALE, v3 * QSCALE);
;       *(uint2*)(p.Q + ((long)(bl * 8 + head) * NTOK + j) * 96 + dd) = o;
;       asm volatile("" ::: "memory");
;     }
.LBB0_902:
	s_or_b64 exec, exec, s[6:7]
	s_mov_b32 s6, 0x3e16c740
	s_waitcnt lgkmcnt(0)
	v_pk_mul_f32 v[12:13], v[22:23], s[6:7] op_sel_hi:[1,0]
	v_pk_mul_f32 v[14:15], v[26:27], s[6:7] op_sel_hi:[1,0]
	v_cvt_pk_bf16_f32 v12, v12, v13
	v_cvt_pk_bf16_f32 v13, v14, v15
	v_lshl_add_u64 v[14:15], v[20:21], 0, v[44:45]
	s_waitcnt lgkmcnt(0)
	v_mov_b64_e32 v[16:17], s[90:91]
	s_movk_i32 s8, 0xc0
	v_mad_u64_u32 v[16:17], s[6:7], v14, s8, v[16:17]
	v_mov_b32_e32 v14, v17
	v_mad_u64_u32 v[14:15], s[6:7], v15, s8, v[14:15]
	v_mov_b32_e32 v17, v14
	v_lshl_add_u64 v[14:15], v[24:25], 1, v[16:17]
	global_store_dwordx2 v[14:15], v[12:13], off
	ds_read_b32 v12, v65 offset:192
	s_waitcnt lgkmcnt(0)
	v_pk_mul_f32 v[16:17], v[8:9], v[12:13] op_sel_hi:[1,0]
	v_pk_mul_f32 v[18:19], v[10:11], v[12:13] op_sel_hi:[1,0]
	s_and_saveexec_b64 s[6:7], s[38:39]
	s_cbranch_execz .LBB0_910
	ds_bpermute_b32 v26, v64, v16
	ds_bpermute_b32 v27, v64, v17
	ds_bpermute_b32 v22, v64, v18
	ds_bpermute_b32 v23, v64, v19
	v_cmp_lt_i32_e64 s[40:41], s67, v40
	s_and_saveexec_b64 s[8:9], s[40:41]
	s_cbranch_execz .LBB0_909
	v_lshlrev_b32_e32 v8, 4, v60
	s_movk_i32 s10, 0x3f0
	v_and_or_b32 v8, v8, s10, v63
	v_lshlrev_b32_e32 v12, 2, v8
	v_add_u32_e32 v12, 0x1f000, v12
	ds_read_b128 v[8:11], v12 offset:16
	s_nop 0
	ds_read_b128 v[12:15], v12
	s_and_saveexec_b64 s[10:11], vcc
	s_xor_b64 s[10:11], exec, s[10:11]
	s_cbranch_execz .LBB0_906
	s_waitcnt lgkmcnt(0)
	v_mov_b32_e32 v28, v13
	v_mov_b32_e32 v29, v15
	s_waitcnt lgkmcnt(2)
	v_pk_mul_f32 v[26:27], v[28:29], v[26:27]
	v_mov_b32_e32 v13, v14
	v_pk_fma_f32 v[16:17], v[16:17], v[12:13], v[26:27]
	v_mov_b32_e32 v12, v9
	v_mov_b32_e32 v13, v11
	s_waitcnt lgkmcnt(0)
	v_pk_mul_f32 v[12:13], v[12:13], v[22:23]
	v_mov_b32_e32 v9, v10
	v_pk_fma_f32 v[18:19], v[18:19], v[8:9], v[12:13]
.LBB0_906:
	s_andn2_saveexec_b64 s[10:11], s[10:11]
	s_cbranch_execz .LBB0_908
	s_waitcnt lgkmcnt(0)
	v_mov_b32_e32 v29, v14
	v_mov_b32_e32 v14, v13
	v_mov_b32_e32 v28, v12
	s_waitcnt lgkmcnt(2)
	v_pk_mul_f32 v[12:13], v[14:15], v[26:27]
	s_nop 0
	v_pk_fma_f32 v[16:17], v[16:17], v[28:29], v[12:13] neg_lo:[0,0,1] neg_hi:[0,0,1]
	v_mov_b32_e32 v13, v10
	v_mov_b32_e32 v10, v9
	v_mov_b32_e32 v12, v8
	s_waitcnt lgkmcnt(0)
	v_pk_mul_f32 v[8:9], v[10:11], v[22:23]
	s_nop 0
	v_pk_fma_f32 v[18:19], v[18:19], v[12:13], v[8:9] neg_lo:[0,0,1] neg_hi:[0,0,1]

; DEV void qproj_item(const Params& p, int l, int tt, int tf, char* smem, int tid) {
;     ...
;   for (int n = 0; n < 2; ++n) {
;     const int fb = f0 + wn * 32 + n * 16;
;     const int head = fb / 96, part = (fb % 96) >> 4;
;     const int dd = part * 16 + fq * 4;
; #pragma unroll
;     for (int t = 0; t < 6; ++t) {
;       const int tl = wt * 96 + t * 16 + fr;
;       const int j = j0 + tl;
;       const float sc = rs[tl];
;       float v0 = acc[n][t][0] * sc, v1 = acc[n][t][1] * sc, v2 = acc[n][t][2] * sc, v3 = acc[n][t][3] * sc;
;       if (part >= 4) {
;         float p0 = shx(v0, 32, lane), p1 = shx(v1, 32, lane), p2 = shx(v2, 32, lane), p3 = shx(v3, 32, lane);
;         if (j >= NCTX) {
;           const int tq = j - NCTX;
;           const int pos = (part == 4) ? (tq >> 6) : (tq & 63);
;           const float* rp = p.rope + (pos * 8 + (fq & 1) * 4) * 2;
;           float4 cs01 = *(const float4*)rp, cs23 = *(const float4*)(rp + 4);
;           if ((fq >> 1) == 0) {
;             v0 = v0 * cs01.x - p0 * cs01.y; v1 = v1 * cs01.z - p1 * cs01.w;
;             v2 = v2 * cs23.x - p2 * cs23.y; v3 = v3 * cs23.z - p3 * cs23.w;
;           } else {
;             v0 = p0 * cs01.y + v0 * cs01.x; v1 = p1 * cs01.w + v1 * cs01.z;
;             v2 = p2 * cs23.y + v2 * cs23.x; v3 = p3 * cs23.w + v3 * cs23.z;
;           }
;         }
;       }
;       uint2 o;
;       o.x = pack2(v0 * QSCALE, v1 * QSCALE);
;       o.y = pack2(v2 * QSCALE, v3 * QSCALE);
;       *(uint2*)(p.Q + ((long)(bl * 8 + head) * NTOK + j) * 96 + dd) = o;
;       asm volatile("" ::: "memory");
;     }
.LBB0_910:
	s_or_b64 exec, exec, s[6:7]
	s_mov_b32 s6, 0x3e16c740
	s_waitcnt lgkmcnt(0)
	v_pk_mul_f32 v[8:9], v[16:17], s[6:7] op_sel_hi:[1,0]
	v_pk_mul_f32 v[10:11], v[18:19], s[6:7] op_sel_hi:[1,0]
	v_cvt_pk_bf16_f32 v8, v8, v9
	v_cvt_pk_bf16_f32 v9, v10, v11
	v_lshl_add_u64 v[10:11], v[20:21], 0, v[40:41]
	s_waitcnt lgkmcnt(0)
	v_mov_b64_e32 v[12:13], s[90:91]
	s_movk_i32 s8, 0xc0
	v_mad_u64_u32 v[12:13], s[6:7], v10, s8, v[12:13]
	v_mov_b32_e32 v10, v13
	v_mad_u64_u32 v[10:11], s[6:7], v11, s8, v[10:11]
	v_mov_b32_e32 v13, v10
	v_lshl_add_u64 v[10:11], v[24:25], 1, v[12:13]
	global_store_dwordx2 v[10:11], v[8:9], off
	ds_read_b32 v8, v65 offset:256
	s_waitcnt lgkmcnt(0)
	v_pk_mul_f32 v[12:13], v[4:5], v[8:9] op_sel_hi:[1,0]
	v_pk_mul_f32 v[14:15], v[6:7], v[8:9] op_sel_hi:[1,0]
	s_and_saveexec_b64 s[6:7], s[38:39]
	s_cbranch_execz .LBB0_918
	ds_bpermute_b32 v18, v64, v12
	ds_bpermute_b32 v19, v64, v13
	ds_bpermute_b32 v16, v64, v14
	ds_bpermute_b32 v17, v64, v15
	v_cmp_lt_i32_e64 s[40:41], s67, v36
	s_and_saveexec_b64 s[8:9], s[40:41]
	s_cbranch_execz .LBB0_917
	v_lshlrev_b32_e32 v4, 4, v62
	s_movk_i32 s10, 0x2f0
	v_and_or_b32 v4, v4, s10, v63
	v_lshlrev_b32_e32 v8, 2, v4
	v_add_u32_e32 v8, 0x1f000, v8
	ds_read_b128 v[4:7], v8 offset:16
	s_nop 0
	ds_read_b128 v[8:11], v8
	s_and_saveexec_b64 s[10:11], vcc
	s_xor_b64 s[10:11], exec, s[10:11]
	s_cbranch_execz .LBB0_914
	s_waitcnt lgkmcnt(0)
	v_mov_b32_e32 v22, v9
	v_mov_b32_e32 v23, v11
	s_waitcnt lgkmcnt(2)
	v_pk_mul_f32 v[18:19], v[22:23], v[18:19]
	v_mov_b32_e32 v9, v10
	v_pk_fma_f32 v[12:13], v[12:13], v[8:9], v[18:19]
	v_mov_b32_e32 v8, v5
	v_mov_b32_e32 v9, v7
	s_waitcnt lgkmcnt(0)
	v_pk_mul_f32 v[8:9], v[8:9], v[16:17]
	v_mov_b32_e32 v5, v6
	v_pk_fma_f32 v[14:15], v[14:15], v[4:5], v[8:9]
.LBB0_914:
	s_andn2_saveexec_b64 s[10:11], s[10:11]
	s_cbranch_execz .LBB0_916
	s_waitcnt lgkmcnt(0)
	v_mov_b32_e32 v23, v10
	v_mov_b32_e32 v10, v9
	v_mov_b32_e32 v22, v8
	s_waitcnt lgkmcnt(2)
	v_pk_mul_f32 v[8:9], v[10:11], v[18:19]
	s_nop 0
	v_pk_fma_f32 v[12:13], v[12:13], v[22:23], v[8:9] neg_lo:[0,0,1] neg_hi:[0,0,1]
	v_mov_b32_e32 v9, v6
	v_mov_b32_e32 v6, v5
	v_mov_b32_e32 v8, v4
	s_waitcnt lgkmcnt(0)
	v_pk_mul_f32 v[4:5], v[6:7], v[16:17]
	s_nop 0
	v_pk_fma_f32 v[14:15], v[14:15], v[8:9], v[4:5] neg_lo:[0,0,1] neg_hi:[0,0,1]

; DEV void qproj_item(const Params& p, int l, int tt, int tf, char* smem, int tid) {
;     ...
;   for (int n = 0; n < 2; ++n) {
;     const int fb = f0 + wn * 32 + n * 16;
;     const int head = fb / 96, part = (fb % 96) >> 4;
;     const int dd = part * 16 + fq * 4;
; #pragma unroll
;     for (int t = 0; t < 6; ++t) {
;       const int tl = wt * 96 + t * 16 + fr;
;       const int j = j0 + tl;
;       const float sc = rs[tl];
;       float v0 = acc[n][t][0] * sc, v1 = acc[n][t][1] * sc, v2 = acc[n][t][2] * sc, v3 = acc[n][t][3] * sc;
;       if (part >= 4) {
;         float p0 = shx(v0, 32, lane), p1 = shx(v1, 32, lane), p2 = shx(v2, 32, lane), p3 = shx(v3, 32, lane);
;         if (j >= NCTX) {
;           const int tq = j - NCTX;
;           const int pos = (part == 4) ? (tq >> 6) : (tq & 63);
;           const float* rp = p.rope + (pos * 8 + (fq & 1) * 4) * 2;
;           float4 cs01 = *(const float4*)rp, cs23 = *(const float4*)(rp + 4);
;           if ((fq >> 1) == 0) {
;             v0 = v0 * cs01.x - p0 * cs01.y; v1 = v1 * cs01.z - p1 * cs01.w;
;             v2 = v2 * cs23.x - p2 * cs23.y; v3 = v3 * cs23.z - p3 * cs23.w;
;           } else {
;             v0 = p0 * cs01.y + v0 * cs01.x; v1 = p1 * cs01.w + v1 * cs01.z;
;             v2 = p2 * cs23.y + v2 * cs23.x; v3 = p3 * cs23.w + v3 * cs23.z;
;           }
;         }
;       }
;       uint2 o;
;       o.x = pack2(v0 * QSCALE, v1 * QSCALE);
;       o.y = pack2(v2 * QSCALE, v3 * QSCALE);
;       *(uint2*)(p.Q + ((long)(bl * 8 + head) * NTOK + j) * 96 + dd) = o;
;       asm volatile("" ::: "memory");
;     }
.LBB0_918:
	s_or_b64 exec, exec, s[6:7]
	s_mov_b32 s6, 0x3e16c740
	s_waitcnt lgkmcnt(0)
	v_pk_mul_f32 v[4:5], v[12:13], s[6:7] op_sel_hi:[1,0]
	v_pk_mul_f32 v[6:7], v[14:15], s[6:7] op_sel_hi:[1,0]
	v_cvt_pk_bf16_f32 v4, v4, v5
	v_cvt_pk_bf16_f32 v5, v6, v7
	v_lshl_add_u64 v[6:7], v[20:21], 0, v[36:37]
	s_waitcnt lgkmcnt(0)
	v_mov_b64_e32 v[8:9], s[90:91]
	s_movk_i32 s8, 0xc0
	v_mad_u64_u32 v[8:9], s[6:7], v6, s8, v[8:9]
	v_mov_b32_e32 v6, v9
	v_mad_u64_u32 v[6:7], s[6:7], v7, s8, v[6:7]
	v_mov_b32_e32 v9, v6
	v_lshl_add_u64 v[6:7], v[24:25], 1, v[8:9]
	global_store_dwordx2 v[6:7], v[4:5], off
	ds_read_b32 v4, v65 offset:320
	s_waitcnt lgkmcnt(0)
	v_pk_mul_f32 v[8:9], v[0:1], v[4:5] op_sel_hi:[1,0]
	v_pk_mul_f32 v[10:11], v[2:3], v[4:5] op_sel_hi:[1,0]
	s_and_saveexec_b64 s[6:7], s[38:39]
	s_cbranch_execz .LBB0_748
	ds_bpermute_b32 v14, v64, v8
	ds_bpermute_b32 v15, v64, v9
	ds_bpermute_b32 v12, v64, v10
	ds_bpermute_b32 v13, v64, v11
	v_cmp_lt_i32_e64 s[38:39], s67, v32
	s_and_saveexec_b64 s[8:9], s[38:39]
	s_cbranch_execz .LBB0_747
	v_lshlrev_b32_e32 v0, 4, v56
	s_movk_i32 s10, 0x3f0
	v_and_or_b32 v0, v0, s10, v63
	v_lshlrev_b32_e32 v4, 2, v0
	v_add_u32_e32 v4, 0x1f000, v4
	ds_read_b128 v[0:3], v4 offset:16
	s_nop 0
	ds_read_b128 v[4:7], v4
	s_and_saveexec_b64 s[10:11], vcc
	s_xor_b64 s[10:11], exec, s[10:11]
	s_cbranch_execz .LBB0_922
	s_waitcnt lgkmcnt(0)
	v_mov_b32_e32 v16, v5
	v_mov_b32_e32 v17, v7
	s_waitcnt lgkmcnt(2)
	v_pk_mul_f32 v[14:15], v[16:17], v[14:15]
	v_mov_b32_e32 v5, v6
	v_pk_fma_f32 v[8:9], v[8:9], v[4:5], v[14:15]
	v_mov_b32_e32 v4, v1
	v_mov_b32_e32 v5, v3
	s_waitcnt lgkmcnt(0)
	v_pk_mul_f32 v[4:5], v[4:5], v[12:13]
	v_mov_b32_e32 v1, v2
	v_pk_fma_f32 v[10:11], v[10:11], v[0:1], v[4:5]
.LBB0_922:
	s_andn2_saveexec_b64 s[10:11], s[10:11]
	s_cbranch_execz .LBB0_746
	s_waitcnt lgkmcnt(0)
	v_mov_b32_e32 v17, v6
	v_mov_b32_e32 v6, v5
	v_mov_b32_e32 v16, v4
	s_waitcnt lgkmcnt(2)
	v_pk_mul_f32 v[4:5], v[6:7], v[14:15]
	s_nop 0
	v_pk_fma_f32 v[8:9], v[8:9], v[16:17], v[4:5] neg_lo:[0,0,1] neg_hi:[0,0,1]
	v_mov_b32_e32 v5, v2
	v_mov_b32_e32 v2, v1
	v_mov_b32_e32 v4, v0
	s_waitcnt lgkmcnt(0)
	v_pk_mul_f32 v[0:1], v[2:3], v[12:13]
	s_nop 0
	v_pk_fma_f32 v[10:11], v[10:11], v[4:5], v[0:1] neg_lo:[0,0,1] neg_hi:[0,0,1]
	s_branch .LBB0_746
